# prompt attention loop: K-tile fetch addresses kept as running pointers (+ per-lane stride) instead of rebuilt from the row index under two exec masks every tile
# baseline (speedup 1.0000x reference)
;     ...
;     auto gload = [&](int t) { const int rb = t == 0 ? r0 : r1 + 64 * (t - 1);
; #pragma unroll
;         for (int i = 0; i < NKC; ++i) { const int e = tid + 512 * i, row = e / CPR, cc = e % CPR;
;             kreg[i] = cc < DN / 8 ? *(const u32x4*)(k1 + (size_t)(rb + row) * ldk1 + 8 * cc) : *(const u32x4*)(k2 + (size_t)(rb + row) * ldk2 + 8 * (cc - DN / 8)); }
;     ...
;         gload(0); lstore(0); if (ntiles > 1) gload(1);
;         __syncthreads();
;         for (int t = 0; t < ntiles; ++t) { const int cur = t & 1;
.LBB0_1906:
	s_lshl_b32 s0, s15, 2
	v_ashrrev_i32_e32 v185, 31, v184
	v_mul_u32_u24_e32 v14, 0x88, v208
	s_add_i32 s13, s13, 5
	s_add_i32 s46, s16, 0x80
	s_sub_i32 s15, 0, s0
	v_add_u32_e32 v4, s46, v183
	v_ashrrev_i32_e32 v5, 31, v4
	s_and_saveexec_b64 s[0:1], s[6:7]
	s_xor_b64 s[0:1], exec, s[0:1]
	v_mad_i64_i32 v[2:3], s[20:21], v4, s96, v[190:191]
	v_lshl_add_u64 v[2:3], v[2:3], 0, s[76:77]
	s_andn2_saveexec_b64 s[0:1], s[0:1]
	v_lshlrev_b64 v[2:3], 10, v[4:5]
	v_lshl_add_u64 v[2:3], v[192:193], 0, v[2:3]
	s_or_b64 exec, exec, s[0:1]
	v_mov_b64_e32 v[248:249], v[2:3]
	v_add_u32_e32 v4, s46, v187
	v_ashrrev_i32_e32 v5, 31, v4
	s_and_saveexec_b64 s[0:1], s[8:9]
	s_xor_b64 s[0:1], exec, s[0:1]
	v_mad_i64_i32 v[2:3], s[20:21], v4, s96, v[194:195]
	v_lshl_add_u64 v[2:3], v[2:3], 0, s[76:77]
	s_andn2_saveexec_b64 s[0:1], s[0:1]
	v_lshlrev_b64 v[2:3], 10, v[4:5]
	v_lshl_add_u64 v[2:3], v[196:197], 0, v[2:3]
	s_or_b64 exec, exec, s[0:1]
	v_mov_b64_e32 v[250:251], v[2:3]
	v_add_u32_e32 v4, s46, v201
	v_ashrrev_i32_e32 v5, 31, v4
	s_and_saveexec_b64 s[0:1], s[10:11]
	s_xor_b64 s[0:1], exec, s[0:1]
	v_mad_i64_i32 v[2:3], s[20:21], v4, s96, v[198:199]
	v_lshl_add_u64 v[2:3], v[2:3], 0, s[76:77]
	s_andn2_saveexec_b64 s[0:1], s[0:1]
	v_lshlrev_b64 v[2:3], 10, v[4:5]
	v_lshl_add_u64 v[2:3], v[202:203], 0, v[2:3]
	s_or_b64 exec, exec, s[0:1]
	v_mov_b64_e32 v[252:253], v[2:3]
	v_mov_b64_e32 v[190:191], v[248:249]
	v_mov_b32_e32 v192, 0x10000
	v_mov_b32_e32 v254, 0x58000
	v_cndmask_b32_e64 v192, v192, v254, s[6:7]
	v_mov_b32_e32 v193, 0
	v_mov_b64_e32 v[194:195], v[250:251]
	v_mov_b32_e32 v196, 0x10000
	v_mov_b32_e32 v254, 0x58000
	v_cndmask_b32_e64 v196, v196, v254, s[8:9]
	v_mov_b32_e32 v197, 0
	v_mov_b64_e32 v[198:199], v[252:253]
	v_mov_b32_e32 v202, 0x10000
	v_mov_b32_e32 v254, 0x58000
	v_cndmask_b32_e64 v202, v202, v254, s[10:11]
	v_mov_b32_e32 v203, 0
	s_movk_i32 s16, 0xff80
	s_waitcnt lgkmcnt(0)
	s_barrier

;     ...
;     auto gload = [&](int t) { const int rb = t == 0 ? r0 : r1 + 64 * (t - 1);
; #pragma unroll
;         for (int i = 0; i < NKC; ++i) { const int e = tid + 512 * i, row = e / CPR, cc = e % CPR;
;             kreg[i] = cc < DN / 8 ? *(const u32x4*)(k1 + (size_t)(rb + row) * ldk1 + 8 * cc) : *(const u32x4*)(k2 + (size_t)(rb + row) * ldk2 + 8 * (cc - DN / 8)); }
; #pragma unroll
;         for (int i = 0; i < 2; ++i) { const int e = tid + 512 * i, d = e >> 3, cc = e & 7; vreg[i] = *(const u32x4*)(vt + (size_t)d * ldvt + rb + 8 * cc); } };
.LBB0_1914:
	global_load_dwordx4 v[160:163], v[190:191], off
	v_lshl_add_u64 v[190:191], v[190:191], 0, v[192:193]
	global_load_dwordx4 v[164:167], v[194:195], off
	v_lshl_add_u64 v[194:195], v[194:195], 0, v[196:197]
	global_load_dwordx4 v[168:171], v[198:199], off
	v_lshl_add_u64 v[198:199], v[198:199], 0, v[202:203]
	s_lshl_b64 s[0:1], s[46:47], 1
	v_lshl_add_u64 v[2:3], v[204:205], 0, s[0:1]
	v_lshl_add_u64 v[4:5], v[206:207], 0, s[0:1]
	global_load_dwordx4 v[172:175], v[2:3], off
	global_load_dwordx4 v[176:179], v[4:5], off
	s_cmp_gt_i32 s18, s12
	s_cbranch_scc0 .LBB0_1910
